# grid-barrier master poll loop back-off s_sleep 2 instead of 1, on top of v047
# speedup vs baseline: 1.0038x; 1.0038x over previous
; __device__ __forceinline__ unsigned xb_ld(unsigned* p)              { return __hip_atomic_load(p, __ATOMIC_RELAXED, __HIP_MEMORY_SCOPE_AGENT); }
; __device__ __forceinline__ void xcd_barrier_complete(unsigned* bar, unsigned x, unsigned& nloc, unsigned& nx) {
;     const unsigned G = gridDim.x * gridDim.y * gridDim.z;
;     unsigned sum, cnt, mine, sp = 0u;
;     for (;;) {
;         sum = 0u; cnt = 0u; mine = 0u;
; #pragma unroll
;         for (unsigned j = 0; j < 16; ++j) { const unsigned c = xb_ld(&bar[XB_XCNT(j)]); sum += c; cnt += (c > 0u) ? 1u : 0u; mine = (j == x) ? c : mine; }
;         if (sum == G) break;
;         __builtin_amdgcn_s_sleep(1);
;         if ((++sp & 255u) == 0u) { if (xb_ld(&bar[XB_TMO])) break; if (sp > XB_SPIN_CAP) { atomicAdd(&bar[XB_TMO], 1u); break; } }
;     }
.LBB0_122:
	v_readlane_b32 s4, v253, 47
	v_readlane_b32 s5, v253, 48
	global_load_dword v8, v0, s[14:15] sc1
	global_load_dword v1, v0, s[16:17] sc1
	s_waitcnt lgkmcnt(0)
	global_load_dword v2, v0, s[18:19] sc1
	global_load_dword v3, v0, s[20:21] sc1
	global_load_dword v4, v0, s[22:23] sc1
	global_load_dword v5, v0, s[50:51] sc1
	global_load_dword v6, v0, s[6:7] sc1
	global_load_dword v7, v0, s[46:47] sc1
	global_load_dword v9, v0, s[4:5] sc1
	v_readlane_b32 s4, v253, 49
	v_readlane_b32 s5, v253, 50
	s_mov_b64 s[26:27], -1
	s_mov_b64 s[36:37], -1
	s_waitcnt vmcnt(7)
	v_add_u32_e32 v17, v1, v8
	s_nop 0
	global_load_dword v10, v0, s[4:5] sc1
	v_readlane_b32 s4, v253, 51
	v_readlane_b32 s5, v253, 52
	s_waitcnt vmcnt(7)
	v_add_u32_e32 v17, v17, v2
	s_waitcnt vmcnt(6)
	v_add_u32_e32 v17, v17, v3
	s_waitcnt vmcnt(5)
	v_add_u32_e32 v17, v17, v4
	s_waitcnt vmcnt(4)
	v_add_u32_e32 v17, v17, v5
	s_waitcnt vmcnt(3)
	v_add_u32_e32 v17, v17, v6
	global_load_dword v11, v0, s[4:5] sc1
	v_readlane_b32 s4, v253, 53
	v_readlane_b32 s5, v253, 54
	s_waitcnt vmcnt(3)
	v_add_u32_e32 v17, v17, v7
	s_waitcnt vmcnt(2)
	v_add_u32_e32 v17, v17, v9
	s_waitcnt vmcnt(1)
	v_add_u32_e32 v17, v17, v10
	global_load_dword v12, v0, s[4:5] sc1
	v_readlane_b32 s4, v253, 55
	v_readlane_b32 s5, v253, 56
	s_waitcnt vmcnt(1)
	v_add_u32_e32 v17, v17, v11
	s_nop 2
	global_load_dword v13, v0, s[4:5] sc1
	v_readlane_b32 s4, v253, 57
	v_readlane_b32 s5, v253, 58
	s_waitcnt vmcnt(1)
	v_add_u32_e32 v17, v17, v12
	s_nop 2
	global_load_dword v14, v0, s[4:5] sc1
	v_readlane_b32 s4, v253, 59
	v_readlane_b32 s5, v253, 60
	s_waitcnt vmcnt(1)
	v_add_u32_e32 v17, v17, v13
	s_nop 2
	global_load_dword v15, v0, s[4:5] sc1
	v_readlane_b32 s4, v253, 61
	v_readlane_b32 s5, v253, 62
	s_waitcnt vmcnt(1)
	v_add_u32_e32 v17, v17, v14
	s_nop 2
	global_load_dword v16, v0, s[4:5] sc1
	s_waitcnt vmcnt(1)
	v_add_u32_e32 v17, v17, v15
	s_waitcnt vmcnt(0)
	v_add_u32_e32 v17, v17, v16
	v_cmp_eq_u32_e32 vcc, s33, v17
	s_cbranch_vccnz .LBB0_121
	s_and_b32 s3, s2, 0xff
	s_cmp_eq_u32 s3, 0
	s_mov_b64 s[38:39], -1
	s_sleep 2
	s_cbranch_scc0 .LBB0_126
	global_load_dword v17, v0, s[12:13] sc1
	s_waitcnt vmcnt(0)
	v_cmp_eq_u32_e32 vcc, 0, v17
	s_cbranch_vccnz .LBB0_128
	s_mov_b64 s[38:39], 0

; __device__ __forceinline__ unsigned xb_ld(unsigned* p)              { return __hip_atomic_load(p, __ATOMIC_RELAXED, __HIP_MEMORY_SCOPE_AGENT); }
; __device__ __forceinline__ void xcd_barrier_complete(unsigned* bar, unsigned x, unsigned& nloc, unsigned& nx) {
;     const unsigned G = gridDim.x * gridDim.y * gridDim.z;
;     unsigned sum, cnt, mine, sp = 0u;
;     for (;;) {
;         sum = 0u; cnt = 0u; mine = 0u;
; #pragma unroll
;         for (unsigned j = 0; j < 16; ++j) { const unsigned c = xb_ld(&bar[XB_XCNT(j)]); sum += c; cnt += (c > 0u) ? 1u : 0u; mine = (j == x) ? c : mine; }
;         if (sum == G) break;
;         __builtin_amdgcn_s_sleep(1);
;         if ((++sp & 255u) == 0u) { if (xb_ld(&bar[XB_TMO])) break; if (sp > XB_SPIN_CAP) { atomicAdd(&bar[XB_TMO], 1u); break; } }
;     }
.LBB0_309:
	v_readlane_b32 s4, v253, 49
	v_readlane_b32 s5, v253, 50
	global_load_dword v9, v0, s[14:15] sc1
	global_load_dword v1, v0, s[16:17] sc1
	s_waitcnt lgkmcnt(0)
	global_load_dword v2, v0, s[18:19] sc1
	global_load_dword v3, v0, s[20:21] sc1
	global_load_dword v4, v0, s[22:23] sc1
	global_load_dword v5, v0, s[50:51] sc1
	global_load_dword v6, v0, s[6:7] sc1
	global_load_dword v7, v0, s[46:47] sc1
	global_load_dword v8, v0, s[48:49] sc1
	global_load_dword v10, v0, s[4:5] sc1
	v_readlane_b32 s4, v253, 51
	v_readlane_b32 s5, v253, 52
	s_mov_b64 s[26:27], -1
	s_mov_b64 s[36:37], -1
	s_waitcnt vmcnt(8)
	v_add_u32_e32 v17, v1, v9
	s_nop 0
	global_load_dword v11, v0, s[4:5] sc1
	v_readlane_b32 s4, v253, 53
	v_readlane_b32 s5, v253, 54
	s_waitcnt vmcnt(8)
	v_add_u32_e32 v17, v17, v2
	s_waitcnt vmcnt(7)
	v_add_u32_e32 v17, v17, v3
	s_waitcnt vmcnt(6)
	v_add_u32_e32 v17, v17, v4
	s_waitcnt vmcnt(5)
	v_add_u32_e32 v17, v17, v5
	s_waitcnt vmcnt(4)
	v_add_u32_e32 v17, v17, v6
	global_load_dword v12, v0, s[4:5] sc1
	v_readlane_b32 s4, v253, 55
	v_readlane_b32 s5, v253, 56
	s_waitcnt vmcnt(4)
	v_add_u32_e32 v17, v17, v7
	s_waitcnt vmcnt(3)
	v_add_u32_e32 v17, v17, v8
	s_waitcnt vmcnt(2)
	v_add_u32_e32 v17, v17, v10
	s_waitcnt vmcnt(1)
	v_add_u32_e32 v17, v17, v11
	global_load_dword v13, v0, s[4:5] sc1
	v_readlane_b32 s4, v253, 57
	v_readlane_b32 s5, v253, 58
	s_waitcnt vmcnt(1)
	v_add_u32_e32 v17, v17, v12
	s_nop 2
	global_load_dword v14, v0, s[4:5] sc1
	v_readlane_b32 s4, v253, 59
	v_readlane_b32 s5, v253, 60
	s_waitcnt vmcnt(1)
	v_add_u32_e32 v17, v17, v13
	s_nop 2
	global_load_dword v15, v0, s[4:5] sc1
	v_readlane_b32 s4, v253, 61
	v_readlane_b32 s5, v253, 62
	s_waitcnt vmcnt(1)
	v_add_u32_e32 v17, v17, v14
	s_nop 2
	global_load_dword v16, v0, s[4:5] sc1
	s_waitcnt vmcnt(1)
	v_add_u32_e32 v17, v17, v15
	s_waitcnt vmcnt(0)
	v_add_u32_e32 v17, v17, v16
	v_cmp_eq_u32_e32 vcc, s33, v17
	s_cbranch_vccnz .LBB0_308
	s_and_b32 s3, s2, 0xff
	s_cmp_eq_u32 s3, 0
	s_mov_b64 s[38:39], -1
	s_sleep 2
	s_cbranch_scc0 .LBB0_313
	global_load_dword v17, v0, s[12:13] sc1
	s_waitcnt vmcnt(0)
	v_cmp_eq_u32_e32 vcc, 0, v17
	s_cbranch_vccnz .LBB0_315
	s_mov_b64 s[38:39], 0

; __device__ __forceinline__ unsigned xb_ld(unsigned* p)              { return __hip_atomic_load(p, __ATOMIC_RELAXED, __HIP_MEMORY_SCOPE_AGENT); }
; __device__ __forceinline__ void xcd_barrier_complete(unsigned* bar, unsigned x, unsigned& nloc, unsigned& nx) {
;     const unsigned G = gridDim.x * gridDim.y * gridDim.z;
;     unsigned sum, cnt, mine, sp = 0u;
;     for (;;) {
;         sum = 0u; cnt = 0u; mine = 0u;
; #pragma unroll
;         for (unsigned j = 0; j < 16; ++j) { const unsigned c = xb_ld(&bar[XB_XCNT(j)]); sum += c; cnt += (c > 0u) ? 1u : 0u; mine = (j == x) ? c : mine; }
;         if (sum == G) break;
;         __builtin_amdgcn_s_sleep(1);
;         if ((++sp & 255u) == 0u) { if (xb_ld(&bar[XB_TMO])) break; if (sp > XB_SPIN_CAP) { atomicAdd(&bar[XB_TMO], 1u); break; } }
;     }
.LBB0_453:
	v_readlane_b32 s4, v253, 49
	v_readlane_b32 s5, v253, 50
	global_load_dword v9, v0, s[14:15] sc1
	global_load_dword v1, v0, s[16:17] sc1
	s_waitcnt lgkmcnt(0)
	global_load_dword v2, v0, s[18:19] sc1
	global_load_dword v3, v0, s[20:21] sc1
	global_load_dword v4, v0, s[22:23] sc1
	global_load_dword v5, v0, s[50:51] sc1
	global_load_dword v6, v0, s[6:7] sc1
	global_load_dword v7, v0, s[46:47] sc1
	global_load_dword v8, v0, s[48:49] sc1
	global_load_dword v10, v0, s[4:5] sc1
	v_readlane_b32 s4, v253, 51
	v_readlane_b32 s5, v253, 52
	s_mov_b64 s[26:27], -1
	s_mov_b64 s[40:41], -1
	s_waitcnt vmcnt(8)
	v_add_u32_e32 v17, v1, v9
	s_nop 0
	global_load_dword v11, v0, s[4:5] sc1
	v_readlane_b32 s4, v253, 53
	v_readlane_b32 s5, v253, 54
	s_waitcnt vmcnt(8)
	v_add_u32_e32 v17, v17, v2
	s_waitcnt vmcnt(7)
	v_add_u32_e32 v17, v17, v3
	s_waitcnt vmcnt(6)
	v_add_u32_e32 v17, v17, v4
	s_waitcnt vmcnt(5)
	v_add_u32_e32 v17, v17, v5
	s_waitcnt vmcnt(4)
	v_add_u32_e32 v17, v17, v6
	global_load_dword v12, v0, s[4:5] sc1
	v_readlane_b32 s4, v253, 55
	v_readlane_b32 s5, v253, 56
	s_waitcnt vmcnt(4)
	v_add_u32_e32 v17, v17, v7
	s_waitcnt vmcnt(3)
	v_add_u32_e32 v17, v17, v8
	s_waitcnt vmcnt(2)
	v_add_u32_e32 v17, v17, v10
	s_waitcnt vmcnt(1)
	v_add_u32_e32 v17, v17, v11
	global_load_dword v13, v0, s[4:5] sc1
	v_readlane_b32 s4, v253, 57
	v_readlane_b32 s5, v253, 58
	s_waitcnt vmcnt(1)
	v_add_u32_e32 v17, v17, v12
	s_nop 2
	global_load_dword v14, v0, s[4:5] sc1
	v_readlane_b32 s4, v253, 59
	v_readlane_b32 s5, v253, 60
	s_waitcnt vmcnt(1)
	v_add_u32_e32 v17, v17, v13
	s_nop 2
	global_load_dword v15, v0, s[4:5] sc1
	v_readlane_b32 s4, v253, 61
	v_readlane_b32 s5, v253, 62
	s_waitcnt vmcnt(1)
	v_add_u32_e32 v17, v17, v14
	s_nop 2
	global_load_dword v16, v0, s[4:5] sc1
	s_waitcnt vmcnt(1)
	v_add_u32_e32 v17, v17, v15
	s_waitcnt vmcnt(0)
	v_add_u32_e32 v17, v17, v16
	v_cmp_eq_u32_e32 vcc, s33, v17
	s_cbranch_vccnz .LBB0_452
	s_and_b32 s3, s2, 0xff
	s_cmp_eq_u32 s3, 0
	s_mov_b64 s[42:43], -1
	s_sleep 2
	s_cbranch_scc0 .LBB0_457
	global_load_dword v17, v0, s[12:13] sc1
	s_waitcnt vmcnt(0)
	v_cmp_eq_u32_e32 vcc, 0, v17
	s_cbranch_vccnz .LBB0_459
	s_mov_b64 s[42:43], 0

; __device__ __forceinline__ unsigned xb_ld(unsigned* p)              { return __hip_atomic_load(p, __ATOMIC_RELAXED, __HIP_MEMORY_SCOPE_AGENT); }
; __device__ __forceinline__ void xcd_barrier_complete(unsigned* bar, unsigned x, unsigned& nloc, unsigned& nx) {
;     const unsigned G = gridDim.x * gridDim.y * gridDim.z;
;     unsigned sum, cnt, mine, sp = 0u;
;     for (;;) {
;         sum = 0u; cnt = 0u; mine = 0u;
; #pragma unroll
;         for (unsigned j = 0; j < 16; ++j) { const unsigned c = xb_ld(&bar[XB_XCNT(j)]); sum += c; cnt += (c > 0u) ? 1u : 0u; mine = (j == x) ? c : mine; }
;         if (sum == G) break;
;         __builtin_amdgcn_s_sleep(1);
;         if ((++sp & 255u) == 0u) { if (xb_ld(&bar[XB_TMO])) break; if (sp > XB_SPIN_CAP) { atomicAdd(&bar[XB_TMO], 1u); break; } }
;     }
.LBB0_527:
	v_readlane_b32 s4, v253, 49
	v_readlane_b32 s5, v253, 50
	global_load_dword v9, v0, s[14:15] sc1
	global_load_dword v1, v0, s[16:17] sc1
	s_waitcnt lgkmcnt(0)
	global_load_dword v2, v0, s[18:19] sc1
	global_load_dword v3, v0, s[20:21] sc1
	global_load_dword v4, v0, s[22:23] sc1
	global_load_dword v5, v0, s[50:51] sc1
	global_load_dword v6, v0, s[6:7] sc1
	global_load_dword v7, v0, s[46:47] sc1
	global_load_dword v8, v0, s[48:49] sc1
	global_load_dword v10, v0, s[4:5] sc1
	v_readlane_b32 s4, v253, 51
	v_readlane_b32 s5, v253, 52
	s_mov_b64 s[26:27], -1
	s_mov_b64 s[38:39], -1
	s_waitcnt vmcnt(8)
	v_add_u32_e32 v17, v1, v9
	s_nop 0
	global_load_dword v11, v0, s[4:5] sc1
	v_readlane_b32 s4, v253, 53
	v_readlane_b32 s5, v253, 54
	s_waitcnt vmcnt(8)
	v_add_u32_e32 v17, v17, v2
	s_waitcnt vmcnt(7)
	v_add_u32_e32 v17, v17, v3
	s_waitcnt vmcnt(6)
	v_add_u32_e32 v17, v17, v4
	s_waitcnt vmcnt(5)
	v_add_u32_e32 v17, v17, v5
	s_waitcnt vmcnt(4)
	v_add_u32_e32 v17, v17, v6
	global_load_dword v12, v0, s[4:5] sc1
	v_readlane_b32 s4, v253, 55
	v_readlane_b32 s5, v253, 56
	s_waitcnt vmcnt(4)
	v_add_u32_e32 v17, v17, v7
	s_waitcnt vmcnt(3)
	v_add_u32_e32 v17, v17, v8
	s_waitcnt vmcnt(2)
	v_add_u32_e32 v17, v17, v10
	s_waitcnt vmcnt(1)
	v_add_u32_e32 v17, v17, v11
	global_load_dword v13, v0, s[4:5] sc1
	v_readlane_b32 s4, v253, 57
	v_readlane_b32 s5, v253, 58
	s_waitcnt vmcnt(1)
	v_add_u32_e32 v17, v17, v12
	s_nop 2
	global_load_dword v14, v0, s[4:5] sc1
	v_readlane_b32 s4, v253, 59
	v_readlane_b32 s5, v253, 60
	s_waitcnt vmcnt(1)
	v_add_u32_e32 v17, v17, v13
	s_nop 2
	global_load_dword v15, v0, s[4:5] sc1
	v_readlane_b32 s4, v253, 61
	v_readlane_b32 s5, v253, 62
	s_waitcnt vmcnt(1)
	v_add_u32_e32 v17, v17, v14
	s_nop 2
	global_load_dword v16, v0, s[4:5] sc1
	s_waitcnt vmcnt(1)
	v_add_u32_e32 v17, v17, v15
	s_waitcnt vmcnt(0)
	v_add_u32_e32 v17, v17, v16
	v_cmp_eq_u32_e32 vcc, s33, v17
	s_cbranch_vccnz .LBB0_526
	s_and_b32 s3, s2, 0xff
	s_cmp_eq_u32 s3, 0
	s_mov_b64 s[40:41], -1
	s_sleep 2
	s_cbranch_scc0 .LBB0_531
	global_load_dword v17, v0, s[12:13] sc1
	s_waitcnt vmcnt(0)
	v_cmp_eq_u32_e32 vcc, 0, v17
	s_cbranch_vccnz .LBB0_533
	s_mov_b64 s[40:41], 0
